# restores the 2-wait-state pad between v_add_co and v_addc at three carry chains in the w_cq row code
# speedup vs baseline: 1.0057x; 1.0057x over previous
.LBB0_216:
	s_waitcnt vmcnt(0)
	v_mov_b64_e32 v[6:7], s[92:93]
	flat_load_dwordx2 v[2:3], v[6:7] offset:64 sc0 sc1
	s_waitcnt vmcnt(0)
	s_lshl_b32 s0, s25, 4
	s_lshl_b32 s1, s24, 1
	s_add_i32 s0, s0, s1
	s_ashr_i32 s1, s0, 31
	s_lshl_b64 s[4:5], s[0:1], 2
	s_lshl_b64 s[6:7], s[0:1], 14
	v_lshlrev_b64 v[8:9], 4, v[134:135]
	v_lshl_add_u64 v[12:13], v[134:135], 3, s[14:15]
	s_lshl_b32 s10, s24, 12
	s_and_b32 s10, s10, 0x1000
	s_waitcnt lgkmcnt(0)
	v_lshl_add_u64 v[2:3], v[2:3], 0, s[4:5]
	flat_load_dword v18, v[2:3]
	global_load_dword v128, v[2:3], off offset:4
	s_nop 0
	flat_load_dwordx2 v[2:3], v[6:7] offset:80 sc0 sc1
	s_waitcnt vmcnt(0) lgkmcnt(0)
	v_lshl_add_u64 v[2:3], v[2:3], 0, s[6:7]
	v_lshl_add_u64 v[10:11], v[2:3], 0, v[8:9]
	v_add_co_u32_e32 v212, vcc, 0x1000, v10
	s_nop 1
	v_addc_co_u32_e32 v213, vcc, 0, v11, vcc
	v_add_co_u32_e32 v228, vcc, 0x2000, v10
	s_nop 1
	v_addc_co_u32_e32 v229, vcc, 0, v11, vcc
	v_add_co_u32_e32 v244, vcc, 0x3000, v10
	s_nop 1
	v_addc_co_u32_e32 v245, vcc, 0, v11, vcc
	global_load_dwordx4 v[184:187], v[10:11], off nt
	global_load_dwordx4 v[188:191], v[10:11], off offset:1024 nt
	global_load_dwordx4 v[192:195], v[10:11], off offset:2048 nt
	global_load_dwordx4 v[196:199], v[10:11], off offset:3072 nt
	global_load_dwordx4 v[200:203], v[212:213], off nt
	global_load_dwordx4 v[204:207], v[212:213], off offset:1024 nt
	global_load_dwordx4 v[208:211], v[212:213], off offset:2048 nt
	global_load_dwordx4 v[212:215], v[212:213], off offset:3072 nt
	global_load_dwordx4 v[216:219], v[228:229], off nt
	global_load_dwordx4 v[220:223], v[228:229], off offset:1024 nt
	global_load_dwordx4 v[224:227], v[228:229], off offset:2048 nt
	global_load_dwordx4 v[228:231], v[228:229], off offset:3072 nt
	global_load_dwordx4 v[232:235], v[244:245], off nt
	global_load_dwordx4 v[236:239], v[244:245], off offset:1024 nt
	global_load_dwordx4 v[240:243], v[244:245], off offset:2048 nt
	global_load_dwordx4 v[244:247], v[244:245], off offset:3072 nt
	v_add_co_u32_e32 v76, vcc, 0x4000, v10
	s_nop 1
	v_addc_co_u32_e32 v77, vcc, 0, v11, vcc
	v_add_co_u32_e32 v92, vcc, 0x5000, v10
	s_nop 1
	v_addc_co_u32_e32 v93, vcc, 0, v11, vcc
	v_add_co_u32_e32 v108, vcc, 0x6000, v10
	s_nop 1
	v_addc_co_u32_e32 v109, vcc, 0, v11, vcc
	v_add_co_u32_e32 v124, vcc, 0x7000, v10
	s_nop 1
	v_addc_co_u32_e32 v125, vcc, 0, v11, vcc
	global_load_dwordx4 v[64:67], v[76:77], off nt
	global_load_dwordx4 v[68:71], v[76:77], off offset:1024 nt
	global_load_dwordx4 v[72:75], v[76:77], off offset:2048 nt
	global_load_dwordx4 v[76:79], v[76:77], off offset:3072 nt
	global_load_dwordx4 v[80:83], v[92:93], off nt
	global_load_dwordx4 v[84:87], v[92:93], off offset:1024 nt
	global_load_dwordx4 v[88:91], v[92:93], off offset:2048 nt
	global_load_dwordx4 v[92:95], v[92:93], off offset:3072 nt
	global_load_dwordx4 v[96:99], v[108:109], off nt
	global_load_dwordx4 v[100:103], v[108:109], off offset:1024 nt
	global_load_dwordx4 v[104:107], v[108:109], off offset:2048 nt
	global_load_dwordx4 v[108:111], v[108:109], off offset:3072 nt
	global_load_dwordx4 v[112:115], v[124:125], off nt
	global_load_dwordx4 v[116:119], v[124:125], off offset:1024 nt
	global_load_dwordx4 v[120:123], v[124:125], off offset:2048 nt
	global_load_dwordx4 v[124:127], v[124:125], off offset:3072 nt
	s_lshl_b64 s[6:7], s[0:1], 13
	v_lshl_add_u64 v[14:15], v[12:13], 0, s[6:7]
	s_movk_i32 s1, 0x1000
	v_add_co_u32_e32 v16, vcc, s1, v10
	s_movk_i32 s6, 0x2000
	s_nop 0
	v_addc_co_u32_e32 v17, vcc, 0, v11, vcc
	s_movk_i32 s7, 0x3000
	s_waitcnt vmcnt(0) lgkmcnt(0)
	v_mov_b32_e32 v2, v184
	v_mov_b32_e32 v3, v185
	v_mov_b32_e32 v4, v186
	v_mov_b32_e32 v5, v187
	v_mul_f32_e32 v2, v18, v2
	v_mul_f32_e32 v3, v18, v3
	v_mul_f32_e32 v4, v18, v4
	v_mul_f32_e32 v5, v18, v5
	v_cvt_pk_bf16_f32 v2, v2, v3
	v_cvt_pk_bf16_f32 v3, v4, v5
	global_store_dwordx2 v[14:15], v[2:3], off
	s_nop 1
	v_mov_b32_e32 v2, v188
	v_mov_b32_e32 v3, v189
	v_mov_b32_e32 v4, v190
	v_mov_b32_e32 v5, v191
	v_mul_f32_e32 v2, v18, v2
	v_mul_f32_e32 v3, v18, v3
	v_mul_f32_e32 v4, v18, v4
	v_mul_f32_e32 v5, v18, v5
	v_cvt_pk_bf16_f32 v2, v2, v3
	v_cvt_pk_bf16_f32 v3, v4, v5
	global_store_dwordx2 v[14:15], v[2:3], off offset:512
	s_nop 1
	v_mov_b32_e32 v2, v192
	v_mov_b32_e32 v3, v193
	v_mov_b32_e32 v4, v194
	v_mov_b32_e32 v5, v195
	v_mul_f32_e32 v2, v18, v2
	v_mul_f32_e32 v3, v18, v3
	v_mul_f32_e32 v4, v18, v4
	v_mul_f32_e32 v5, v18, v5
	v_cvt_pk_bf16_f32 v2, v2, v3
	v_cvt_pk_bf16_f32 v3, v4, v5
	global_store_dwordx2 v[14:15], v[2:3], off offset:1024
	s_nop 1
	v_mov_b32_e32 v2, v196
	v_mov_b32_e32 v3, v197
	v_mov_b32_e32 v4, v198
	v_mov_b32_e32 v5, v199
	v_mul_f32_e32 v2, v18, v2
	v_mul_f32_e32 v3, v18, v3
	v_mul_f32_e32 v4, v18, v4
	v_mul_f32_e32 v5, v18, v5
	v_cvt_pk_bf16_f32 v2, v2, v3
	v_cvt_pk_bf16_f32 v3, v4, v5
	global_store_dwordx2 v[14:15], v[2:3], off offset:1536
	s_nop 1
	v_mov_b32_e32 v2, v200
	v_mov_b32_e32 v3, v201
	v_mov_b32_e32 v4, v202
	v_mov_b32_e32 v5, v203
	v_mul_f32_e32 v2, v18, v2
	v_mul_f32_e32 v3, v18, v3
	v_mul_f32_e32 v4, v18, v4
	v_mul_f32_e32 v5, v18, v5
	v_cvt_pk_bf16_f32 v2, v2, v3
	v_cvt_pk_bf16_f32 v3, v4, v5
	global_store_dwordx2 v[14:15], v[2:3], off offset:2048
	s_nop 1
	v_mov_b32_e32 v2, v204
	v_mov_b32_e32 v3, v205
	v_mov_b32_e32 v4, v206
	v_mov_b32_e32 v5, v207
	v_mul_f32_e32 v2, v18, v2
	v_mul_f32_e32 v3, v18, v3
	v_mul_f32_e32 v4, v18, v4
	v_mul_f32_e32 v5, v18, v5
	v_cvt_pk_bf16_f32 v2, v2, v3
	v_cvt_pk_bf16_f32 v3, v4, v5
	global_store_dwordx2 v[14:15], v[2:3], off offset:2560
	s_nop 1
	v_mov_b32_e32 v2, v208
	v_mov_b32_e32 v3, v209
	v_mov_b32_e32 v4, v210
	v_mov_b32_e32 v5, v211
	v_mul_f32_e32 v2, v18, v2
	v_mul_f32_e32 v3, v18, v3
	v_mul_f32_e32 v4, v18, v4
	v_mul_f32_e32 v5, v18, v5
	v_cvt_pk_bf16_f32 v2, v2, v3
	v_cvt_pk_bf16_f32 v3, v4, v5
	global_store_dwordx2 v[14:15], v[2:3], off offset:3072
	s_nop 1
	v_mov_b32_e32 v2, v212
	v_mov_b32_e32 v3, v213
	v_mov_b32_e32 v4, v214
	v_mov_b32_e32 v5, v215
	v_add_co_u32_e32 v16, vcc, s6, v10
	v_mul_f32_e32 v2, v18, v2
	v_mul_f32_e32 v3, v18, v3
	v_addc_co_u32_e32 v17, vcc, 0, v11, vcc
	v_mul_f32_e32 v4, v18, v4
	v_mul_f32_e32 v5, v18, v5
	v_cvt_pk_bf16_f32 v2, v2, v3
	v_cvt_pk_bf16_f32 v3, v4, v5
	global_store_dwordx2 v[14:15], v[2:3], off offset:3584
	s_nop 1
	v_mov_b32_e32 v2, v216
	v_mov_b32_e32 v3, v217
	v_mov_b32_e32 v4, v218
	v_mov_b32_e32 v5, v219
	v_add_co_u32_e32 v14, vcc, s1, v14
	v_mul_f32_e32 v2, v18, v2
	s_nop 0
	v_addc_co_u32_e32 v15, vcc, 0, v15, vcc
	v_mul_f32_e32 v3, v18, v3
	v_mul_f32_e32 v4, v18, v4
	v_mul_f32_e32 v5, v18, v5
	v_cvt_pk_bf16_f32 v2, v2, v3
	v_cvt_pk_bf16_f32 v3, v4, v5
	global_store_dwordx2 v[14:15], v[2:3], off
	s_nop 1
	v_mov_b32_e32 v2, v220
	v_mov_b32_e32 v3, v221
	v_mov_b32_e32 v4, v222
	v_mov_b32_e32 v5, v223
	v_add_co_u32_e32 v10, vcc, s7, v10
	v_mul_f32_e32 v2, v18, v2
	v_mul_f32_e32 v3, v18, v3
	v_mul_f32_e32 v4, v18, v4
	v_mul_f32_e32 v5, v18, v5
	v_cvt_pk_bf16_f32 v2, v2, v3
	v_cvt_pk_bf16_f32 v3, v4, v5
	global_store_dwordx2 v[14:15], v[2:3], off offset:512
	s_nop 1
	v_mov_b32_e32 v2, v224
	v_mov_b32_e32 v3, v225
	v_mov_b32_e32 v4, v226
	v_mov_b32_e32 v5, v227
	v_addc_co_u32_e32 v11, vcc, 0, v11, vcc
	v_mul_f32_e32 v2, v18, v2
	v_mul_f32_e32 v3, v18, v3
	v_mul_f32_e32 v4, v18, v4
	v_mul_f32_e32 v5, v18, v5
	v_cvt_pk_bf16_f32 v2, v2, v3
	v_cvt_pk_bf16_f32 v3, v4, v5
	global_store_dwordx2 v[14:15], v[2:3], off offset:1024
	s_nop 1
	v_mov_b32_e32 v2, v228
	v_mov_b32_e32 v3, v229
	v_mov_b32_e32 v4, v230
	v_mov_b32_e32 v5, v231
	v_mul_f32_e32 v2, v18, v2
	v_mul_f32_e32 v3, v18, v3
	v_mul_f32_e32 v4, v18, v4
	v_mul_f32_e32 v5, v18, v5
	v_cvt_pk_bf16_f32 v2, v2, v3
	v_cvt_pk_bf16_f32 v3, v4, v5
	global_store_dwordx2 v[14:15], v[2:3], off offset:1536
	s_nop 1
	v_mov_b32_e32 v2, v232
	v_mov_b32_e32 v3, v233
	v_mov_b32_e32 v4, v234
	v_mov_b32_e32 v5, v235
	v_mul_f32_e32 v2, v18, v2
	v_mul_f32_e32 v3, v18, v3
	v_mul_f32_e32 v4, v18, v4
	v_mul_f32_e32 v5, v18, v5
	v_cvt_pk_bf16_f32 v2, v2, v3
	v_cvt_pk_bf16_f32 v3, v4, v5
	global_store_dwordx2 v[14:15], v[2:3], off offset:2048
	s_nop 1
	v_mov_b32_e32 v2, v236
	v_mov_b32_e32 v3, v237
	v_mov_b32_e32 v4, v238
	v_mov_b32_e32 v5, v239
	v_mul_f32_e32 v2, v18, v2
	v_mul_f32_e32 v3, v18, v3
	v_mul_f32_e32 v4, v18, v4
	v_mul_f32_e32 v5, v18, v5
	v_cvt_pk_bf16_f32 v2, v2, v3
	v_cvt_pk_bf16_f32 v3, v4, v5
	global_store_dwordx2 v[14:15], v[2:3], off offset:2560
	s_nop 1
	v_mov_b32_e32 v2, v240
	v_mov_b32_e32 v3, v241
	v_mov_b32_e32 v4, v242
	v_mov_b32_e32 v5, v243
	v_mul_f32_e32 v2, v18, v2
	v_mul_f32_e32 v3, v18, v3
	v_mul_f32_e32 v4, v18, v4
	v_mul_f32_e32 v5, v18, v5
	v_cvt_pk_bf16_f32 v2, v2, v3
	v_cvt_pk_bf16_f32 v3, v4, v5
	global_store_dwordx2 v[14:15], v[2:3], off offset:3072
	s_nop 1
	v_mov_b32_e32 v2, v244
	v_mov_b32_e32 v3, v245
	v_mov_b32_e32 v4, v246
	v_mov_b32_e32 v5, v247
	v_mul_f32_e32 v2, v18, v2
	v_mul_f32_e32 v3, v18, v3
	v_mul_f32_e32 v4, v18, v4
	v_mul_f32_e32 v5, v18, v5
	v_cvt_pk_bf16_f32 v2, v2, v3
	v_cvt_pk_bf16_f32 v3, v4, v5
	global_store_dwordx2 v[14:15], v[2:3], off offset:3584
	v_lshl_add_u64 v[2:3], v[2:3], 0, s[4:5]
	s_nop 0
	s_or_b32 s4, s0, 1
	s_ashr_i32 s5, s4, 31
	s_lshl_b64 s[8:9], s[4:5], 14
	s_lshl_b64 s[4:5], s[4:5], 13
	s_waitcnt lgkmcnt(0)
	v_lshl_add_u64 v[2:3], v[2:3], 0, s[8:9]
	v_lshl_add_u64 v[6:7], v[2:3], 0, v[8:9]
	v_lshl_add_u64 v[8:9], v[12:13], 0, s[4:5]
	v_add_co_u32_e32 v10, vcc, s1, v6
	s_add_i32 s4, s24, s57
	s_nop 0
	v_addc_co_u32_e32 v11, vcc, 0, v7, vcc
	s_lshl_b32 s4, s4, 3
	s_mov_b64 s[8:9], 0x26000100
	s_movk_i32 s5, 0xffe0
	s_waitcnt vmcnt(16) lgkmcnt(0)
	v_mov_b32_e32 v20, v128
	v_mov_b32_e32 v2, v64
	v_mov_b32_e32 v3, v65
	v_mov_b32_e32 v4, v66
	v_mov_b32_e32 v5, v67
	v_mul_f32_e32 v2, v20, v2
	v_mul_f32_e32 v3, v20, v3
	v_mul_f32_e32 v4, v20, v4
	v_mul_f32_e32 v5, v20, v5
	v_cvt_pk_bf16_f32 v2, v2, v3
	v_cvt_pk_bf16_f32 v3, v4, v5
	global_store_dwordx2 v[8:9], v[2:3], off
	s_nop 1
	v_mov_b32_e32 v2, v68
	v_mov_b32_e32 v3, v69
	v_mov_b32_e32 v4, v70
	v_mov_b32_e32 v5, v71
	v_mul_f32_e32 v2, v20, v2
	v_mul_f32_e32 v3, v20, v3
	v_mul_f32_e32 v4, v20, v4
	v_mul_f32_e32 v5, v20, v5
	v_cvt_pk_bf16_f32 v2, v2, v3
	v_cvt_pk_bf16_f32 v3, v4, v5
	global_store_dwordx2 v[8:9], v[2:3], off offset:512
	s_nop 1
	v_mov_b32_e32 v2, v72
	v_mov_b32_e32 v3, v73
	v_mov_b32_e32 v4, v74
	v_mov_b32_e32 v5, v75
	v_mul_f32_e32 v2, v20, v2
	v_mul_f32_e32 v3, v20, v3
	v_mul_f32_e32 v4, v20, v4
	v_mul_f32_e32 v5, v20, v5
	v_cvt_pk_bf16_f32 v2, v2, v3
	v_cvt_pk_bf16_f32 v3, v4, v5
	global_store_dwordx2 v[8:9], v[2:3], off offset:1024
	s_nop 1
	v_mov_b32_e32 v2, v76
	v_mov_b32_e32 v3, v77
	v_mov_b32_e32 v4, v78
	v_mov_b32_e32 v5, v79
	v_mul_f32_e32 v2, v20, v2
	v_mul_f32_e32 v3, v20, v3
	v_mul_f32_e32 v4, v20, v4
	v_mul_f32_e32 v5, v20, v5
	v_cvt_pk_bf16_f32 v2, v2, v3
	v_cvt_pk_bf16_f32 v3, v4, v5
	global_store_dwordx2 v[8:9], v[2:3], off offset:1536
	s_nop 1
	v_mov_b32_e32 v2, v80
	v_mov_b32_e32 v3, v81
	v_mov_b32_e32 v4, v82
	v_mov_b32_e32 v5, v83
	v_mul_f32_e32 v2, v20, v2
	v_mul_f32_e32 v3, v20, v3
	v_mul_f32_e32 v4, v20, v4
	v_mul_f32_e32 v5, v20, v5
	v_cvt_pk_bf16_f32 v2, v2, v3
	v_cvt_pk_bf16_f32 v3, v4, v5
	global_store_dwordx2 v[8:9], v[2:3], off offset:2048
	s_nop 1
	v_mov_b32_e32 v2, v84
	v_mov_b32_e32 v3, v85
	v_mov_b32_e32 v4, v86
	v_mov_b32_e32 v5, v87
	v_mul_f32_e32 v2, v20, v2
	v_mul_f32_e32 v3, v20, v3
	v_mul_f32_e32 v4, v20, v4
	v_mul_f32_e32 v5, v20, v5
	v_cvt_pk_bf16_f32 v2, v2, v3
	v_cvt_pk_bf16_f32 v3, v4, v5
	global_store_dwordx2 v[8:9], v[2:3], off offset:2560
	s_nop 1
	v_mov_b32_e32 v2, v88
	v_mov_b32_e32 v3, v89
	v_mov_b32_e32 v4, v90
	v_mov_b32_e32 v5, v91
	v_mul_f32_e32 v2, v20, v2
	v_mul_f32_e32 v3, v20, v3
	v_mul_f32_e32 v4, v20, v4
	v_mul_f32_e32 v5, v20, v5
	v_cvt_pk_bf16_f32 v2, v2, v3
	v_cvt_pk_bf16_f32 v3, v4, v5
	global_store_dwordx2 v[8:9], v[2:3], off offset:3072
	s_nop 1
	v_mov_b32_e32 v2, v92
	v_mov_b32_e32 v3, v93
	v_mov_b32_e32 v4, v94
	v_mov_b32_e32 v5, v95
	v_add_co_u32_e32 v10, vcc, s6, v6
	v_mul_f32_e32 v2, v20, v2
	v_mul_f32_e32 v3, v20, v3
	v_addc_co_u32_e32 v11, vcc, 0, v7, vcc
	v_mul_f32_e32 v4, v20, v4
	v_mul_f32_e32 v5, v20, v5
	v_cvt_pk_bf16_f32 v2, v2, v3
	v_cvt_pk_bf16_f32 v3, v4, v5
	global_store_dwordx2 v[8:9], v[2:3], off offset:3584
	s_nop 1
	v_mov_b32_e32 v2, v96
	v_mov_b32_e32 v3, v97
	v_mov_b32_e32 v4, v98
	v_mov_b32_e32 v5, v99
	v_add_co_u32_e32 v16, vcc, s1, v8
	v_lshlrev_b32_e32 v8, 3, v150
	s_nop 0
	v_addc_co_u32_e32 v17, vcc, 0, v9, vcc
	v_add_co_u32_e32 v6, vcc, s7, v6
	v_ashrrev_i32_e32 v9, 31, v8
	s_nop 0
	v_addc_co_u32_e32 v7, vcc, 0, v7, vcc
	v_lshlrev_b64 v[18:19], 1, v[8:9]
	s_mov_b64 s[6:7], 0x4e500100
	s_mov_b64 s[0:1], 0x200
	v_mul_f32_e32 v2, v20, v2
	v_mul_f32_e32 v3, v20, v3
	v_mul_f32_e32 v4, v20, v4
	v_mul_f32_e32 v5, v20, v5
	v_cvt_pk_bf16_f32 v2, v2, v3
	v_cvt_pk_bf16_f32 v3, v4, v5
	global_store_dwordx2 v[16:17], v[2:3], off
	s_nop 1
	v_mov_b32_e32 v2, v100
	v_mov_b32_e32 v3, v101
	v_mov_b32_e32 v4, v102
	v_mov_b32_e32 v5, v103
	v_mul_f32_e32 v2, v20, v2
	v_mul_f32_e32 v3, v20, v3
	v_mul_f32_e32 v4, v20, v4
	v_mul_f32_e32 v5, v20, v5
	v_cvt_pk_bf16_f32 v2, v2, v3
	v_cvt_pk_bf16_f32 v3, v4, v5
	global_store_dwordx2 v[16:17], v[2:3], off offset:512
	s_nop 1
	v_mov_b32_e32 v2, v104
	v_mov_b32_e32 v3, v105
	v_mov_b32_e32 v4, v106
	v_mov_b32_e32 v5, v107
	v_mul_f32_e32 v2, v20, v2
	v_mul_f32_e32 v3, v20, v3
	v_mul_f32_e32 v4, v20, v4
	v_mul_f32_e32 v5, v20, v5
	v_cvt_pk_bf16_f32 v2, v2, v3
	v_cvt_pk_bf16_f32 v3, v4, v5
	global_store_dwordx2 v[16:17], v[2:3], off offset:1024
	s_nop 1
	v_mov_b32_e32 v2, v108
	v_mov_b32_e32 v3, v109
	v_mov_b32_e32 v4, v110
	v_mov_b32_e32 v5, v111
	v_bfi_b32 v10, -16, s4, v134
	v_ashrrev_i32_e32 v11, 31, v10
	v_lshlrev_b64 v[10:11], 13, v[10:11]
	v_or_b32_e32 v10, s10, v10
	v_lshl_add_u64 v[10:11], v[10:11], 0, v[18:19]
	v_lshl_add_u64 v[10:11], s[78:79], 0, v[10:11]
	v_lshl_add_u64 v[10:11], v[10:11], 0, s[8:9]
	v_mul_f32_e32 v2, v20, v2
	v_mul_f32_e32 v3, v20, v3
	v_mul_f32_e32 v4, v20, v4
	v_mul_f32_e32 v5, v20, v5
	v_cvt_pk_bf16_f32 v2, v2, v3
	v_cvt_pk_bf16_f32 v3, v4, v5
	global_store_dwordx2 v[16:17], v[2:3], off offset:1536
	s_nop 1
	v_mov_b32_e32 v2, v112
	v_mov_b32_e32 v3, v113
	v_mov_b32_e32 v4, v114
	v_mov_b32_e32 v5, v115
	v_mul_f32_e32 v2, v20, v2
	v_mul_f32_e32 v3, v20, v3
	v_mul_f32_e32 v4, v20, v4
	v_mul_f32_e32 v5, v20, v5
	v_cvt_pk_bf16_f32 v2, v2, v3
	v_cvt_pk_bf16_f32 v3, v4, v5
	global_store_dwordx2 v[16:17], v[2:3], off offset:2048
	s_nop 1
	v_mov_b32_e32 v2, v116
	v_mov_b32_e32 v3, v117
	v_mov_b32_e32 v4, v118
	v_mov_b32_e32 v5, v119
	v_mul_f32_e32 v2, v20, v2
	v_mul_f32_e32 v3, v20, v3
	v_mul_f32_e32 v4, v20, v4
	v_mul_f32_e32 v5, v20, v5
	v_cvt_pk_bf16_f32 v2, v2, v3
	v_cvt_pk_bf16_f32 v3, v4, v5
	global_store_dwordx2 v[16:17], v[2:3], off offset:2560
	s_nop 1
	v_mov_b32_e32 v2, v120
	v_mov_b32_e32 v3, v121
	v_mov_b32_e32 v4, v122
	v_mov_b32_e32 v5, v123
	v_mul_f32_e32 v2, v20, v2
	v_mul_f32_e32 v3, v20, v3
	v_mul_f32_e32 v4, v20, v4
	v_mul_f32_e32 v5, v20, v5
	v_cvt_pk_bf16_f32 v2, v2, v3
	v_cvt_pk_bf16_f32 v3, v4, v5
	global_store_dwordx2 v[16:17], v[2:3], off offset:3072
	s_nop 1
	v_mov_b32_e32 v12, v124
	v_mov_b32_e32 v13, v125
	v_mov_b32_e32 v14, v126
	v_mov_b32_e32 v15, v127
	v_and_b32_e32 v6, 15, v134
	v_mov_b32_e32 v3, 0
	v_lshl_or_b32 v2, v6, 13, s10
	v_lshl_add_u64 v[8:9], v[2:3], 0, v[18:19]
	v_lshl_add_u64 v[8:9], s[78:79], 0, v[8:9]
	v_mov_b32_e32 v4, v3
	v_mov_b32_e32 v2, v3
	v_lshl_add_u64 v[8:9], v[8:9], 0, s[6:7]
	v_mul_f32_e32 v5, v20, v12
	v_mul_f32_e32 v7, v20, v13
	v_mul_f32_e32 v13, v20, v14
	v_cvt_pk_bf16_f32 v12, v5, v7
	v_mov_b32_e32 v5, v3
	v_mul_f32_e32 v14, v20, v15
	v_cvt_pk_bf16_f32 v13, v13, v14
	global_store_dwordx2 v[16:17], v[12:13], off offset:3584

.LBB0_328:
	s_waitcnt vmcnt(0)
	v_mov_b64_e32 v[6:7], s[92:93]
	flat_load_dwordx2 v[2:3], v[6:7] offset:64 sc0 sc1
	s_waitcnt vmcnt(0)
	s_lshl_b32 s0, s27, 4
	s_lshl_b32 s1, s26, 1
	s_add_i32 s0, s0, s1
	s_ashr_i32 s1, s0, 31
	s_lshl_b64 s[6:7], s[0:1], 2
	s_lshl_b64 s[8:9], s[0:1], 14
	v_lshlrev_b64 v[8:9], 4, v[134:135]
	v_lshl_add_u64 v[12:13], v[134:135], 3, s[14:15]
	s_lshl_b32 s12, s26, 12
	s_and_b32 s12, s12, 0x1000
	s_waitcnt lgkmcnt(0)
	v_lshl_add_u64 v[2:3], v[2:3], 0, s[6:7]
	flat_load_dword v18, v[2:3]
	global_load_dword v128, v[2:3], off offset:4
	s_nop 0
	flat_load_dwordx2 v[2:3], v[6:7] offset:80 sc0 sc1
	s_waitcnt vmcnt(0) lgkmcnt(0)
	v_lshl_add_u64 v[2:3], v[2:3], 0, s[8:9]
	v_lshl_add_u64 v[10:11], v[2:3], 0, v[8:9]
	v_add_co_u32_e32 v212, vcc, 0x1000, v10
	s_nop 1
	v_addc_co_u32_e32 v213, vcc, 0, v11, vcc
	v_add_co_u32_e32 v228, vcc, 0x2000, v10
	s_nop 1
	v_addc_co_u32_e32 v229, vcc, 0, v11, vcc
	v_add_co_u32_e32 v244, vcc, 0x3000, v10
	s_nop 1
	v_addc_co_u32_e32 v245, vcc, 0, v11, vcc
	global_load_dwordx4 v[184:187], v[10:11], off nt
	global_load_dwordx4 v[188:191], v[10:11], off offset:1024 nt
	global_load_dwordx4 v[192:195], v[10:11], off offset:2048 nt
	global_load_dwordx4 v[196:199], v[10:11], off offset:3072 nt
	global_load_dwordx4 v[200:203], v[212:213], off nt
	global_load_dwordx4 v[204:207], v[212:213], off offset:1024 nt
	global_load_dwordx4 v[208:211], v[212:213], off offset:2048 nt
	global_load_dwordx4 v[212:215], v[212:213], off offset:3072 nt
	global_load_dwordx4 v[216:219], v[228:229], off nt
	global_load_dwordx4 v[220:223], v[228:229], off offset:1024 nt
	global_load_dwordx4 v[224:227], v[228:229], off offset:2048 nt
	global_load_dwordx4 v[228:231], v[228:229], off offset:3072 nt
	global_load_dwordx4 v[232:235], v[244:245], off nt
	global_load_dwordx4 v[236:239], v[244:245], off offset:1024 nt
	global_load_dwordx4 v[240:243], v[244:245], off offset:2048 nt
	global_load_dwordx4 v[244:247], v[244:245], off offset:3072 nt
	v_add_co_u32_e32 v76, vcc, 0x4000, v10
	s_nop 1
	v_addc_co_u32_e32 v77, vcc, 0, v11, vcc
	v_add_co_u32_e32 v92, vcc, 0x5000, v10
	s_nop 1
	v_addc_co_u32_e32 v93, vcc, 0, v11, vcc
	v_add_co_u32_e32 v108, vcc, 0x6000, v10
	s_nop 1
	v_addc_co_u32_e32 v109, vcc, 0, v11, vcc
	v_add_co_u32_e32 v124, vcc, 0x7000, v10
	s_nop 1
	v_addc_co_u32_e32 v125, vcc, 0, v11, vcc
	global_load_dwordx4 v[64:67], v[76:77], off nt
	global_load_dwordx4 v[68:71], v[76:77], off offset:1024 nt
	global_load_dwordx4 v[72:75], v[76:77], off offset:2048 nt
	global_load_dwordx4 v[76:79], v[76:77], off offset:3072 nt
	global_load_dwordx4 v[80:83], v[92:93], off nt
	global_load_dwordx4 v[84:87], v[92:93], off offset:1024 nt
	global_load_dwordx4 v[88:91], v[92:93], off offset:2048 nt
	global_load_dwordx4 v[92:95], v[92:93], off offset:3072 nt
	global_load_dwordx4 v[96:99], v[108:109], off nt
	global_load_dwordx4 v[100:103], v[108:109], off offset:1024 nt
	global_load_dwordx4 v[104:107], v[108:109], off offset:2048 nt
	global_load_dwordx4 v[108:111], v[108:109], off offset:3072 nt
	global_load_dwordx4 v[112:115], v[124:125], off nt
	global_load_dwordx4 v[116:119], v[124:125], off offset:1024 nt
	global_load_dwordx4 v[120:123], v[124:125], off offset:2048 nt
	global_load_dwordx4 v[124:127], v[124:125], off offset:3072 nt
	s_lshl_b64 s[8:9], s[0:1], 13
	v_lshl_add_u64 v[14:15], v[12:13], 0, s[8:9]
	s_movk_i32 s1, 0x1000
	v_add_co_u32_e32 v16, vcc, s1, v10
	s_movk_i32 s8, 0x2000
	s_nop 0
	v_addc_co_u32_e32 v17, vcc, 0, v11, vcc
	s_movk_i32 s9, 0x3000
	s_waitcnt vmcnt(0) lgkmcnt(0)
	v_mov_b32_e32 v2, v184
	v_mov_b32_e32 v3, v185
	v_mov_b32_e32 v4, v186
	v_mov_b32_e32 v5, v187
	v_mul_f32_e32 v2, v18, v2
	v_mul_f32_e32 v3, v18, v3
	v_mul_f32_e32 v4, v18, v4
	v_mul_f32_e32 v5, v18, v5
	v_cvt_pk_bf16_f32 v2, v2, v3
	v_cvt_pk_bf16_f32 v3, v4, v5
	global_store_dwordx2 v[14:15], v[2:3], off
	s_nop 1
	v_mov_b32_e32 v2, v188
	v_mov_b32_e32 v3, v189
	v_mov_b32_e32 v4, v190
	v_mov_b32_e32 v5, v191
	v_mul_f32_e32 v2, v18, v2
	v_mul_f32_e32 v3, v18, v3
	v_mul_f32_e32 v4, v18, v4
	v_mul_f32_e32 v5, v18, v5
	v_cvt_pk_bf16_f32 v2, v2, v3
	v_cvt_pk_bf16_f32 v3, v4, v5
	global_store_dwordx2 v[14:15], v[2:3], off offset:512
	s_nop 1
	v_mov_b32_e32 v2, v192
	v_mov_b32_e32 v3, v193
	v_mov_b32_e32 v4, v194
	v_mov_b32_e32 v5, v195
	v_mul_f32_e32 v2, v18, v2
	v_mul_f32_e32 v3, v18, v3
	v_mul_f32_e32 v4, v18, v4
	v_mul_f32_e32 v5, v18, v5
	v_cvt_pk_bf16_f32 v2, v2, v3
	v_cvt_pk_bf16_f32 v3, v4, v5
	global_store_dwordx2 v[14:15], v[2:3], off offset:1024
	s_nop 1
	v_mov_b32_e32 v2, v196
	v_mov_b32_e32 v3, v197
	v_mov_b32_e32 v4, v198
	v_mov_b32_e32 v5, v199
	v_mul_f32_e32 v2, v18, v2
	v_mul_f32_e32 v3, v18, v3
	v_mul_f32_e32 v4, v18, v4
	v_mul_f32_e32 v5, v18, v5
	v_cvt_pk_bf16_f32 v2, v2, v3
	v_cvt_pk_bf16_f32 v3, v4, v5
	global_store_dwordx2 v[14:15], v[2:3], off offset:1536
	s_nop 1
	v_mov_b32_e32 v2, v200
	v_mov_b32_e32 v3, v201
	v_mov_b32_e32 v4, v202
	v_mov_b32_e32 v5, v203
	v_mul_f32_e32 v2, v18, v2
	v_mul_f32_e32 v3, v18, v3
	v_mul_f32_e32 v4, v18, v4
	v_mul_f32_e32 v5, v18, v5
	v_cvt_pk_bf16_f32 v2, v2, v3
	v_cvt_pk_bf16_f32 v3, v4, v5
	global_store_dwordx2 v[14:15], v[2:3], off offset:2048
	s_nop 1
	v_mov_b32_e32 v2, v204
	v_mov_b32_e32 v3, v205
	v_mov_b32_e32 v4, v206
	v_mov_b32_e32 v5, v207
	v_mul_f32_e32 v2, v18, v2
	v_mul_f32_e32 v3, v18, v3
	v_mul_f32_e32 v4, v18, v4
	v_mul_f32_e32 v5, v18, v5
	v_cvt_pk_bf16_f32 v2, v2, v3
	v_cvt_pk_bf16_f32 v3, v4, v5
	global_store_dwordx2 v[14:15], v[2:3], off offset:2560
	s_nop 1
	v_mov_b32_e32 v2, v208
	v_mov_b32_e32 v3, v209
	v_mov_b32_e32 v4, v210
	v_mov_b32_e32 v5, v211
	v_mul_f32_e32 v2, v18, v2
	v_mul_f32_e32 v3, v18, v3
	v_mul_f32_e32 v4, v18, v4
	v_mul_f32_e32 v5, v18, v5
	v_cvt_pk_bf16_f32 v2, v2, v3
	v_cvt_pk_bf16_f32 v3, v4, v5
	global_store_dwordx2 v[14:15], v[2:3], off offset:3072
	s_nop 1
	v_mov_b32_e32 v2, v212
	v_mov_b32_e32 v3, v213
	v_mov_b32_e32 v4, v214
	v_mov_b32_e32 v5, v215
	v_add_co_u32_e32 v16, vcc, s8, v10
	v_mul_f32_e32 v2, v18, v2
	v_mul_f32_e32 v3, v18, v3
	v_addc_co_u32_e32 v17, vcc, 0, v11, vcc
	v_mul_f32_e32 v4, v18, v4
	v_mul_f32_e32 v5, v18, v5
	v_cvt_pk_bf16_f32 v2, v2, v3
	v_cvt_pk_bf16_f32 v3, v4, v5
	global_store_dwordx2 v[14:15], v[2:3], off offset:3584
	s_nop 1
	v_mov_b32_e32 v2, v216
	v_mov_b32_e32 v3, v217
	v_mov_b32_e32 v4, v218
	v_mov_b32_e32 v5, v219
	v_add_co_u32_e32 v14, vcc, s1, v14
	v_mul_f32_e32 v2, v18, v2
	s_nop 0
	v_addc_co_u32_e32 v15, vcc, 0, v15, vcc
	v_mul_f32_e32 v3, v18, v3
	v_mul_f32_e32 v4, v18, v4
	v_mul_f32_e32 v5, v18, v5
	v_cvt_pk_bf16_f32 v2, v2, v3
	v_cvt_pk_bf16_f32 v3, v4, v5
	global_store_dwordx2 v[14:15], v[2:3], off
	s_nop 1
	v_mov_b32_e32 v2, v220
	v_mov_b32_e32 v3, v221
	v_mov_b32_e32 v4, v222
	v_mov_b32_e32 v5, v223
	v_add_co_u32_e32 v10, vcc, s9, v10
	v_mul_f32_e32 v2, v18, v2
	v_mul_f32_e32 v3, v18, v3
	v_mul_f32_e32 v4, v18, v4
	v_mul_f32_e32 v5, v18, v5
	v_cvt_pk_bf16_f32 v2, v2, v3
	v_cvt_pk_bf16_f32 v3, v4, v5
	global_store_dwordx2 v[14:15], v[2:3], off offset:512
	s_nop 1
	v_mov_b32_e32 v2, v224
	v_mov_b32_e32 v3, v225
	v_mov_b32_e32 v4, v226
	v_mov_b32_e32 v5, v227
	v_addc_co_u32_e32 v11, vcc, 0, v11, vcc
	v_mul_f32_e32 v2, v18, v2
	v_mul_f32_e32 v3, v18, v3
	v_mul_f32_e32 v4, v18, v4
	v_mul_f32_e32 v5, v18, v5
	v_cvt_pk_bf16_f32 v2, v2, v3
	v_cvt_pk_bf16_f32 v3, v4, v5
	global_store_dwordx2 v[14:15], v[2:3], off offset:1024
	s_nop 1
	v_mov_b32_e32 v2, v228
	v_mov_b32_e32 v3, v229
	v_mov_b32_e32 v4, v230
	v_mov_b32_e32 v5, v231
	v_mul_f32_e32 v2, v18, v2
	v_mul_f32_e32 v3, v18, v3
	v_mul_f32_e32 v4, v18, v4
	v_mul_f32_e32 v5, v18, v5
	v_cvt_pk_bf16_f32 v2, v2, v3
	v_cvt_pk_bf16_f32 v3, v4, v5
	global_store_dwordx2 v[14:15], v[2:3], off offset:1536
	s_nop 1
	v_mov_b32_e32 v2, v232
	v_mov_b32_e32 v3, v233
	v_mov_b32_e32 v4, v234
	v_mov_b32_e32 v5, v235
	v_mul_f32_e32 v2, v18, v2
	v_mul_f32_e32 v3, v18, v3
	v_mul_f32_e32 v4, v18, v4
	v_mul_f32_e32 v5, v18, v5
	v_cvt_pk_bf16_f32 v2, v2, v3
	v_cvt_pk_bf16_f32 v3, v4, v5
	global_store_dwordx2 v[14:15], v[2:3], off offset:2048
	s_nop 1
	v_mov_b32_e32 v2, v236
	v_mov_b32_e32 v3, v237
	v_mov_b32_e32 v4, v238
	v_mov_b32_e32 v5, v239
	v_mul_f32_e32 v2, v18, v2
	v_mul_f32_e32 v3, v18, v3
	v_mul_f32_e32 v4, v18, v4
	v_mul_f32_e32 v5, v18, v5
	v_cvt_pk_bf16_f32 v2, v2, v3
	v_cvt_pk_bf16_f32 v3, v4, v5
	global_store_dwordx2 v[14:15], v[2:3], off offset:2560
	s_nop 1
	v_mov_b32_e32 v2, v240
	v_mov_b32_e32 v3, v241
	v_mov_b32_e32 v4, v242
	v_mov_b32_e32 v5, v243
	v_mul_f32_e32 v2, v18, v2
	v_mul_f32_e32 v3, v18, v3
	v_mul_f32_e32 v4, v18, v4
	v_mul_f32_e32 v5, v18, v5
	v_cvt_pk_bf16_f32 v2, v2, v3
	v_cvt_pk_bf16_f32 v3, v4, v5
	global_store_dwordx2 v[14:15], v[2:3], off offset:3072
	s_nop 1
	v_mov_b32_e32 v2, v244
	v_mov_b32_e32 v3, v245
	v_mov_b32_e32 v4, v246
	v_mov_b32_e32 v5, v247
	v_mul_f32_e32 v2, v18, v2
	v_mul_f32_e32 v3, v18, v3
	v_mul_f32_e32 v4, v18, v4
	v_mul_f32_e32 v5, v18, v5
	v_cvt_pk_bf16_f32 v2, v2, v3
	v_cvt_pk_bf16_f32 v3, v4, v5
	global_store_dwordx2 v[14:15], v[2:3], off offset:3584
	v_lshl_add_u64 v[2:3], v[2:3], 0, s[6:7]
	s_nop 0
	s_or_b32 s6, s0, 1
	s_ashr_i32 s7, s6, 31
	s_lshl_b64 s[10:11], s[6:7], 14
	s_lshl_b64 s[6:7], s[6:7], 13
	s_waitcnt lgkmcnt(0)
	v_lshl_add_u64 v[2:3], v[2:3], 0, s[10:11]
	v_lshl_add_u64 v[6:7], v[2:3], 0, v[8:9]
	v_lshl_add_u64 v[8:9], v[12:13], 0, s[6:7]
	v_add_co_u32_e32 v10, vcc, s1, v6
	s_add_i32 s6, s26, s57
	s_nop 0
	v_addc_co_u32_e32 v11, vcc, 0, v7, vcc
	s_lshl_b32 s6, s6, 3
	s_mov_b64 s[10:11], 0x26000100
	s_movk_i32 s7, 0xffe0
	s_waitcnt vmcnt(16) lgkmcnt(0)
	v_mov_b32_e32 v20, v128
	v_mov_b32_e32 v2, v64
	v_mov_b32_e32 v3, v65
	v_mov_b32_e32 v4, v66
	v_mov_b32_e32 v5, v67
	v_mul_f32_e32 v2, v20, v2
	v_mul_f32_e32 v3, v20, v3
	v_mul_f32_e32 v4, v20, v4
	v_mul_f32_e32 v5, v20, v5
	v_cvt_pk_bf16_f32 v2, v2, v3
	v_cvt_pk_bf16_f32 v3, v4, v5
	global_store_dwordx2 v[8:9], v[2:3], off
	s_nop 1
	v_mov_b32_e32 v2, v68
	v_mov_b32_e32 v3, v69
	v_mov_b32_e32 v4, v70
	v_mov_b32_e32 v5, v71
	v_mul_f32_e32 v2, v20, v2
	v_mul_f32_e32 v3, v20, v3
	v_mul_f32_e32 v4, v20, v4
	v_mul_f32_e32 v5, v20, v5
	v_cvt_pk_bf16_f32 v2, v2, v3
	v_cvt_pk_bf16_f32 v3, v4, v5
	global_store_dwordx2 v[8:9], v[2:3], off offset:512
	s_nop 1
	v_mov_b32_e32 v2, v72
	v_mov_b32_e32 v3, v73
	v_mov_b32_e32 v4, v74
	v_mov_b32_e32 v5, v75
	v_mul_f32_e32 v2, v20, v2
	v_mul_f32_e32 v3, v20, v3
	v_mul_f32_e32 v4, v20, v4
	v_mul_f32_e32 v5, v20, v5
	v_cvt_pk_bf16_f32 v2, v2, v3
	v_cvt_pk_bf16_f32 v3, v4, v5
	global_store_dwordx2 v[8:9], v[2:3], off offset:1024
	s_nop 1
	v_mov_b32_e32 v2, v76
	v_mov_b32_e32 v3, v77
	v_mov_b32_e32 v4, v78
	v_mov_b32_e32 v5, v79
	v_mul_f32_e32 v2, v20, v2
	v_mul_f32_e32 v3, v20, v3
	v_mul_f32_e32 v4, v20, v4
	v_mul_f32_e32 v5, v20, v5
	v_cvt_pk_bf16_f32 v2, v2, v3
	v_cvt_pk_bf16_f32 v3, v4, v5
	global_store_dwordx2 v[8:9], v[2:3], off offset:1536
	s_nop 1
	v_mov_b32_e32 v2, v80
	v_mov_b32_e32 v3, v81
	v_mov_b32_e32 v4, v82
	v_mov_b32_e32 v5, v83
	v_mul_f32_e32 v2, v20, v2
	v_mul_f32_e32 v3, v20, v3
	v_mul_f32_e32 v4, v20, v4
	v_mul_f32_e32 v5, v20, v5
	v_cvt_pk_bf16_f32 v2, v2, v3
	v_cvt_pk_bf16_f32 v3, v4, v5
	global_store_dwordx2 v[8:9], v[2:3], off offset:2048
	s_nop 1
	v_mov_b32_e32 v2, v84
	v_mov_b32_e32 v3, v85
	v_mov_b32_e32 v4, v86
	v_mov_b32_e32 v5, v87
	v_mul_f32_e32 v2, v20, v2
	v_mul_f32_e32 v3, v20, v3
	v_mul_f32_e32 v4, v20, v4
	v_mul_f32_e32 v5, v20, v5
	v_cvt_pk_bf16_f32 v2, v2, v3
	v_cvt_pk_bf16_f32 v3, v4, v5
	global_store_dwordx2 v[8:9], v[2:3], off offset:2560
	s_nop 1
	v_mov_b32_e32 v2, v88
	v_mov_b32_e32 v3, v89
	v_mov_b32_e32 v4, v90
	v_mov_b32_e32 v5, v91
	v_mul_f32_e32 v2, v20, v2
	v_mul_f32_e32 v3, v20, v3
	v_mul_f32_e32 v4, v20, v4
	v_mul_f32_e32 v5, v20, v5
	v_cvt_pk_bf16_f32 v2, v2, v3
	v_cvt_pk_bf16_f32 v3, v4, v5
	global_store_dwordx2 v[8:9], v[2:3], off offset:3072
	s_nop 1
	v_mov_b32_e32 v2, v92
	v_mov_b32_e32 v3, v93
	v_mov_b32_e32 v4, v94
	v_mov_b32_e32 v5, v95
	v_add_co_u32_e32 v10, vcc, s8, v6
	v_mul_f32_e32 v2, v20, v2
	v_mul_f32_e32 v3, v20, v3
	v_addc_co_u32_e32 v11, vcc, 0, v7, vcc
	v_mul_f32_e32 v4, v20, v4
	v_mul_f32_e32 v5, v20, v5
	v_cvt_pk_bf16_f32 v2, v2, v3
	v_cvt_pk_bf16_f32 v3, v4, v5
	global_store_dwordx2 v[8:9], v[2:3], off offset:3584
	s_nop 1
	v_mov_b32_e32 v2, v96
	v_mov_b32_e32 v3, v97
	v_mov_b32_e32 v4, v98
	v_mov_b32_e32 v5, v99
	v_add_co_u32_e32 v16, vcc, s1, v8
	v_lshlrev_b32_e32 v8, 3, v150
	s_nop 0
	v_addc_co_u32_e32 v17, vcc, 0, v9, vcc
	v_add_co_u32_e32 v6, vcc, s9, v6
	v_ashrrev_i32_e32 v9, 31, v8
	s_nop 0
	v_addc_co_u32_e32 v7, vcc, 0, v7, vcc
	v_lshlrev_b64 v[18:19], 1, v[8:9]
	s_mov_b64 s[8:9], 0x4e500100
	s_mov_b64 s[0:1], 0x200
	v_mul_f32_e32 v2, v20, v2
	v_mul_f32_e32 v3, v20, v3
	v_mul_f32_e32 v4, v20, v4
	v_mul_f32_e32 v5, v20, v5
	v_cvt_pk_bf16_f32 v2, v2, v3
	v_cvt_pk_bf16_f32 v3, v4, v5
	global_store_dwordx2 v[16:17], v[2:3], off
	s_nop 1
	v_mov_b32_e32 v2, v100
	v_mov_b32_e32 v3, v101
	v_mov_b32_e32 v4, v102
	v_mov_b32_e32 v5, v103
	v_mul_f32_e32 v2, v20, v2
	v_mul_f32_e32 v3, v20, v3
	v_mul_f32_e32 v4, v20, v4
	v_mul_f32_e32 v5, v20, v5
	v_cvt_pk_bf16_f32 v2, v2, v3
	v_cvt_pk_bf16_f32 v3, v4, v5
	global_store_dwordx2 v[16:17], v[2:3], off offset:512
	s_nop 1
	v_mov_b32_e32 v2, v104
	v_mov_b32_e32 v3, v105
	v_mov_b32_e32 v4, v106
	v_mov_b32_e32 v5, v107
	v_mul_f32_e32 v2, v20, v2
	v_mul_f32_e32 v3, v20, v3
	v_mul_f32_e32 v4, v20, v4
	v_mul_f32_e32 v5, v20, v5
	v_cvt_pk_bf16_f32 v2, v2, v3
	v_cvt_pk_bf16_f32 v3, v4, v5
	global_store_dwordx2 v[16:17], v[2:3], off offset:1024
	s_nop 1
	v_mov_b32_e32 v2, v108
	v_mov_b32_e32 v3, v109
	v_mov_b32_e32 v4, v110
	v_mov_b32_e32 v5, v111
	v_bfi_b32 v10, -16, s6, v134
	v_ashrrev_i32_e32 v11, 31, v10
	v_lshlrev_b64 v[10:11], 13, v[10:11]
	v_or_b32_e32 v10, s12, v10
	v_lshl_add_u64 v[10:11], v[10:11], 0, v[18:19]
	v_lshl_add_u64 v[10:11], s[78:79], 0, v[10:11]
	v_lshl_add_u64 v[10:11], v[10:11], 0, s[10:11]
	v_mul_f32_e32 v2, v20, v2
	v_mul_f32_e32 v3, v20, v3
	v_mul_f32_e32 v4, v20, v4
	v_mul_f32_e32 v5, v20, v5
	v_cvt_pk_bf16_f32 v2, v2, v3
	v_cvt_pk_bf16_f32 v3, v4, v5
	global_store_dwordx2 v[16:17], v[2:3], off offset:1536
	s_nop 1
	v_mov_b32_e32 v2, v112
	v_mov_b32_e32 v3, v113
	v_mov_b32_e32 v4, v114
	v_mov_b32_e32 v5, v115
	v_mul_f32_e32 v2, v20, v2
	v_mul_f32_e32 v3, v20, v3
	v_mul_f32_e32 v4, v20, v4
	v_mul_f32_e32 v5, v20, v5
	v_cvt_pk_bf16_f32 v2, v2, v3
	v_cvt_pk_bf16_f32 v3, v4, v5
	global_store_dwordx2 v[16:17], v[2:3], off offset:2048
	s_nop 1
	v_mov_b32_e32 v2, v116
	v_mov_b32_e32 v3, v117
	v_mov_b32_e32 v4, v118
	v_mov_b32_e32 v5, v119
	v_mul_f32_e32 v2, v20, v2
	v_mul_f32_e32 v3, v20, v3
	v_mul_f32_e32 v4, v20, v4
	v_mul_f32_e32 v5, v20, v5
	v_cvt_pk_bf16_f32 v2, v2, v3
	v_cvt_pk_bf16_f32 v3, v4, v5
	global_store_dwordx2 v[16:17], v[2:3], off offset:2560
	s_nop 1
	v_mov_b32_e32 v2, v120
	v_mov_b32_e32 v3, v121
	v_mov_b32_e32 v4, v122
	v_mov_b32_e32 v5, v123
	v_mul_f32_e32 v2, v20, v2
	v_mul_f32_e32 v3, v20, v3
	v_mul_f32_e32 v4, v20, v4
	v_mul_f32_e32 v5, v20, v5
	v_cvt_pk_bf16_f32 v2, v2, v3
	v_cvt_pk_bf16_f32 v3, v4, v5
	global_store_dwordx2 v[16:17], v[2:3], off offset:3072
	s_nop 1
	v_mov_b32_e32 v12, v124
	v_mov_b32_e32 v13, v125
	v_mov_b32_e32 v14, v126
	v_mov_b32_e32 v15, v127
	v_and_b32_e32 v6, 15, v134
	v_mov_b32_e32 v3, 0
	v_lshl_or_b32 v2, v6, 13, s12
	v_lshl_add_u64 v[8:9], v[2:3], 0, v[18:19]
	v_lshl_add_u64 v[8:9], s[78:79], 0, v[8:9]
	v_mov_b32_e32 v4, v3
	v_mov_b32_e32 v2, v3
	v_lshl_add_u64 v[8:9], v[8:9], 0, s[8:9]
	v_mul_f32_e32 v5, v20, v12
	v_mul_f32_e32 v7, v20, v13
	v_mul_f32_e32 v13, v20, v14
	v_cvt_pk_bf16_f32 v12, v5, v7
	v_mov_b32_e32 v5, v3
	v_mul_f32_e32 v14, v20, v15
	v_cvt_pk_bf16_f32 v13, v13, v14
	global_store_dwordx2 v[16:17], v[12:13], off offset:3584
